# in-proj main GEMM: first K-loop iteration peeled with C=0 first-touch MFMAs; the 128 accumulator-zeroing moves per unit removed
# baseline (speedup 1.0000x reference)
.LBB0_697:
	s_ashr_i32 s45, s44, 31
	s_lshl_b64 s[4:5], s[44:45], 19
	v_readlane_b32 s24, v254, 43
	v_readlane_b32 s25, v254, 44
	s_add_u32 s4, s24, s4
	s_addc_u32 s5, s25, s5
	s_and_b64 s[24:25], s[40:41], exec
	s_cselect_b32 s24, s5, s7
	s_cselect_b32 s25, s4, s6
	s_ashr_i32 s39, s38, 31
	s_lshl_b64 s[28:29], s[38:39], 19
	s_add_u32 s48, s11, s28
	s_addc_u32 s49, s12, s29
	s_and_b64 s[28:29], s[40:41], exec
	s_cselect_b32 s28, s49, s1
	s_cselect_b32 s29, s48, s0
	s_add_u32 s56, s6, 0x40080
	s_addc_u32 s57, s7, 0
	s_add_u32 s34, s0, 0x100
	s_addc_u32 s35, s1, 0
	s_mov_b32 s39, -2
	s_waitcnt vmcnt(0)
	s_mov_b64 s[60:61], 0x80
	s_add_u32 s0, s56, 0xfffc0080
	s_addc_u32 s1, s57, -1
	s_add_i32 s43, 0, 0x10000
	s_cmp_eq_u32 s39, 12
	s_cselect_b32 s7, s24, s1
	s_cselect_b32 s6, s25, s0
	s_cselect_b32 s1, s28, s35
	s_cselect_b32 s0, s29, s34
	s_add_i32 s45, 0, 0x14000
	v_add_u32_e32 v152, s43, v175
	v_add_u32_e32 v182, s45, v175
	ds_read_b128 v[140:143], v152
	ds_read_b128 v[144:147], v152 offset:1024
	ds_read_b128 v[148:151], v152 offset:2048
	ds_read_b128 v[152:155], v152 offset:3072
	ds_read_b128 v[156:159], v182
	ds_read_b128 v[170:173], v182 offset:1024
	ds_read_b128 v[178:181], v182 offset:2048
	ds_read_b128 v[182:185], v182 offset:3072
	v_lshl_add_u64 v[206:207], s[56:57], 0, v[136:137]
	s_add_i32 m0, s13, 0xc000
	ds_read_b128 v[186:189], v177
	ds_read_b128 v[190:193], v177 offset:1024
	ds_read_b128 v[194:197], v177 offset:2048
	ds_read_b128 v[198:201], v177 offset:3072
	ds_read_b128 v[202:205], v177 offset:4096
	ds_read_b128 v[224:227], v177 offset:5120
	ds_read_b128 v[228:231], v177 offset:6144
	ds_read_b128 v[232:235], v177 offset:7168
	global_load_lds_dwordx4 v[206:207], off
	v_lshl_add_u64 v[206:207], s[56:57], 0, v[138:139]
	s_add_i32 m0, s13, 0xe000
	s_nop 0
	global_load_lds_dwordx4 v[206:207], off
	s_cmp_lg_u32 s39, -2
	s_cbranch_scc1 .Lpwt__698_0
	s_cmp_lt_u32 s23, 2
	s_cbranch_scc0 .Lpws__698_0

.Lpws__698_0:
	s_waitcnt lgkmcnt(0)
	s_barrier
	s_setprio 1
	s_waitcnt lgkmcnt(0)
	v_mfma_f32_16x16x32_bf16 v[126:129], v[140:143], v[186:189], 0
	v_mfma_f32_16x16x32_bf16 v[122:125], v[148:151], v[186:189], 0
	v_mfma_f32_16x16x32_bf16 v[110:113], v[140:143], v[194:197], 0
	v_mfma_f32_16x16x32_bf16 v[106:109], v[148:151], v[194:197], 0
	v_mfma_f32_16x16x32_bf16 v[94:97], v[140:143], v[202:205], 0
	v_mfma_f32_16x16x32_bf16 v[90:93], v[148:151], v[202:205], 0
	v_mfma_f32_16x16x32_bf16 v[78:81], v[140:143], v[228:231], 0
	v_mfma_f32_16x16x32_bf16 v[74:77], v[148:151], v[228:231], 0
	v_mfma_f32_16x16x32_bf16 v[126:129], v[144:147], v[190:193], v[126:129]
	v_mfma_f32_16x16x32_bf16 v[122:125], v[152:155], v[190:193], v[122:125]
	v_mfma_f32_16x16x32_bf16 v[110:113], v[144:147], v[198:201], v[110:113]
	v_mfma_f32_16x16x32_bf16 v[106:109], v[152:155], v[198:201], v[106:109]
	v_mfma_f32_16x16x32_bf16 v[94:97], v[144:147], v[224:227], v[94:97]
	v_mfma_f32_16x16x32_bf16 v[90:93], v[152:155], v[224:227], v[90:93]
	v_mfma_f32_16x16x32_bf16 v[78:81], v[144:147], v[232:235], v[78:81]
	v_mfma_f32_16x16x32_bf16 v[74:77], v[152:155], v[232:235], v[74:77]
	s_setprio 0
	s_setprio 1
	v_mfma_f32_16x16x32_bf16 v[118:121], v[156:159], v[186:189], 0
	v_mfma_f32_16x16x32_bf16 v[114:117], v[178:181], v[186:189], 0
	v_mfma_f32_16x16x32_bf16 v[102:105], v[156:159], v[194:197], 0
	v_mfma_f32_16x16x32_bf16 v[98:101], v[178:181], v[194:197], 0
	v_mfma_f32_16x16x32_bf16 v[86:89], v[156:159], v[202:205], 0
	v_mfma_f32_16x16x32_bf16 v[82:85], v[178:181], v[202:205], 0
	v_mfma_f32_16x16x32_bf16 v[70:73], v[156:159], v[228:231], 0
	v_mfma_f32_16x16x32_bf16 v[66:69], v[178:181], v[228:231], 0
	v_mfma_f32_16x16x32_bf16 v[118:121], v[170:173], v[190:193], v[118:121]
	v_mfma_f32_16x16x32_bf16 v[114:117], v[182:185], v[190:193], v[114:117]
	v_mfma_f32_16x16x32_bf16 v[102:105], v[170:173], v[198:201], v[102:105]
	v_mfma_f32_16x16x32_bf16 v[98:101], v[182:185], v[198:201], v[98:101]
	v_mfma_f32_16x16x32_bf16 v[86:89], v[170:173], v[224:227], v[86:89]
	v_mfma_f32_16x16x32_bf16 v[82:85], v[182:185], v[224:227], v[82:85]
	v_mfma_f32_16x16x32_bf16 v[70:73], v[170:173], v[232:235], v[70:73]
	v_mfma_f32_16x16x32_bf16 v[66:69], v[182:185], v[232:235], v[66:69]
	s_setprio 0
	s_barrier
	s_add_i32 s43, s43, s10
	v_lshl_add_u64 v[206:207], s[0:1], 0, v[0:1]
	s_mov_b32 m0, s43
	ds_read_b128 v[186:189], v177 offset:16384
	ds_read_b128 v[190:193], v177 offset:17408
	ds_read_b128 v[194:197], v177 offset:18432
	ds_read_b128 v[198:201], v177 offset:19456
	ds_read_b128 v[202:205], v177 offset:20480
	ds_read_b128 v[224:227], v177 offset:21504
	ds_read_b128 v[228:231], v177 offset:22528
	ds_read_b128 v[232:235], v177 offset:23552
	global_load_lds_dwordx4 v[206:207], off
	s_add_i32 m0, s43, 0x2000
	s_add_u32 s46, s0, 0x40000
	v_lshl_add_u64 v[236:237], s[0:1], 0, v[134:135]
	s_addc_u32 s47, s1, 0
	s_add_i32 s43, s45, s10
	global_load_lds_dwordx4 v[236:237], off
	v_lshl_add_u64 v[238:239], s[46:47], 0, v[0:1]
	s_mov_b32 m0, s43
	v_lshl_add_u64 v[240:241], s[6:7], 0, v[132:133]
	global_load_lds_dwordx4 v[238:239], off
	v_lshl_add_u64 v[238:239], s[46:47], 0, v[134:135]
	s_add_i32 m0, s43, 0x2000
	s_nop 0
	global_load_lds_dwordx4 v[238:239], off
	v_lshl_add_u64 v[238:239], s[6:7], 0, v[130:131]
	s_mov_b32 m0, s13
	s_nop 0
	global_load_lds_dwordx4 v[238:239], off
	s_mov_b32 m0, s14
	s_nop 0
	global_load_lds_dwordx4 v[240:241], off
	s_cmp_lg_u32 s39, -2
	s_cbranch_scc1 .Lpwt__698_1
	s_cmp_lt_u32 s23, 2
	s_cbranch_scc0 .Lpws__698_1

.Lpws__698_1:
	s_waitcnt lgkmcnt(0)
	s_barrier
	s_setprio 1
	s_waitcnt lgkmcnt(0)
	v_mfma_f32_16x16x32_bf16 v[62:65], v[140:143], v[186:189], 0
	v_mfma_f32_16x16x32_bf16 v[58:61], v[148:151], v[186:189], 0
	v_mfma_f32_16x16x32_bf16 v[46:49], v[140:143], v[194:197], 0
	v_mfma_f32_16x16x32_bf16 v[42:45], v[148:151], v[194:197], 0
	v_mfma_f32_16x16x32_bf16 v[30:33], v[140:143], v[202:205], 0
	v_mfma_f32_16x16x32_bf16 v[26:29], v[148:151], v[202:205], 0
	v_mfma_f32_16x16x32_bf16 v[14:17], v[140:143], v[228:231], 0
	v_mfma_f32_16x16x32_bf16 v[10:13], v[148:151], v[228:231], 0
	v_mfma_f32_16x16x32_bf16 v[62:65], v[144:147], v[190:193], v[62:65]
	v_mfma_f32_16x16x32_bf16 v[58:61], v[152:155], v[190:193], v[58:61]
	v_mfma_f32_16x16x32_bf16 v[46:49], v[144:147], v[198:201], v[46:49]
	v_mfma_f32_16x16x32_bf16 v[42:45], v[152:155], v[198:201], v[42:45]
	v_mfma_f32_16x16x32_bf16 v[30:33], v[144:147], v[224:227], v[30:33]
	v_mfma_f32_16x16x32_bf16 v[26:29], v[152:155], v[224:227], v[26:29]
	v_mfma_f32_16x16x32_bf16 v[14:17], v[144:147], v[232:235], v[14:17]
	v_mfma_f32_16x16x32_bf16 v[10:13], v[152:155], v[232:235], v[10:13]
	s_setprio 0
	s_setprio 1
	v_mfma_f32_16x16x32_bf16 v[54:57], v[156:159], v[186:189], 0
	v_mfma_f32_16x16x32_bf16 v[50:53], v[178:181], v[186:189], 0
	v_mfma_f32_16x16x32_bf16 v[38:41], v[156:159], v[194:197], 0
	v_mfma_f32_16x16x32_bf16 v[34:37], v[178:181], v[194:197], 0
	v_mfma_f32_16x16x32_bf16 v[22:25], v[156:159], v[202:205], 0
	v_mfma_f32_16x16x32_bf16 v[18:21], v[178:181], v[202:205], 0
	v_mfma_f32_16x16x32_bf16 v[6:9], v[156:159], v[228:231], 0
	v_mfma_f32_16x16x32_bf16 v[2:5], v[178:181], v[228:231], 0
	v_mfma_f32_16x16x32_bf16 v[54:57], v[170:173], v[190:193], v[54:57]
	v_mfma_f32_16x16x32_bf16 v[50:53], v[182:185], v[190:193], v[50:53]
	v_mfma_f32_16x16x32_bf16 v[38:41], v[170:173], v[198:201], v[38:41]
	v_mfma_f32_16x16x32_bf16 v[34:37], v[182:185], v[198:201], v[34:37]
	v_mfma_f32_16x16x32_bf16 v[22:25], v[170:173], v[224:227], v[22:25]
	v_mfma_f32_16x16x32_bf16 v[18:21], v[182:185], v[224:227], v[18:21]
	v_mfma_f32_16x16x32_bf16 v[6:9], v[170:173], v[232:235], v[6:9]
	v_mfma_f32_16x16x32_bf16 v[2:5], v[182:185], v[232:235], v[2:5]
	s_setprio 0
	s_barrier
	s_add_i32 s43, 0, 0x18000
	s_add_i32 s45, 0, 0x1c000
	v_add_u32_e32 v152, s43, v175
	v_add_u32_e32 v182, s45, v175
	ds_read_b128 v[140:143], v152
	ds_read_b128 v[144:147], v152 offset:1024
	ds_read_b128 v[148:151], v152 offset:2048
	ds_read_b128 v[152:155], v152 offset:3072
	ds_read_b128 v[156:159], v182
	ds_read_b128 v[170:173], v182 offset:1024
	ds_read_b128 v[178:181], v182 offset:2048
	ds_read_b128 v[182:185], v182 offset:3072
	s_add_u32 s6, s6, 0x40000
	s_addc_u32 s7, s7, 0
	s_mov_b32 m0, s15
	v_lshl_add_u64 v[242:243], s[6:7], 0, v[130:131]
	ds_read_b128 v[186:189], v177 offset:32768
	ds_read_b128 v[190:193], v177 offset:33792
	ds_read_b128 v[194:197], v177 offset:34816
	ds_read_b128 v[198:201], v177 offset:35840
	ds_read_b128 v[202:205], v177 offset:36864
	ds_read_b128 v[224:227], v177 offset:37888
	ds_read_b128 v[228:231], v177 offset:38912
	ds_read_b128 v[232:235], v177 offset:39936
	global_load_lds_dwordx4 v[242:243], off
	v_lshl_add_u64 v[242:243], s[6:7], 0, v[132:133]
	s_mov_b32 m0, s16
	s_nop 0
	global_load_lds_dwordx4 v[242:243], off
	s_waitcnt vmcnt(8)
	s_waitcnt lgkmcnt(0)
	s_barrier
	s_setprio 1
	s_waitcnt lgkmcnt(0)
	v_mfma_f32_16x16x32_bf16 v[126:129], v[140:143], v[186:189], v[126:129]
	v_mfma_f32_16x16x32_bf16 v[122:125], v[148:151], v[186:189], v[122:125]
	v_mfma_f32_16x16x32_bf16 v[110:113], v[140:143], v[194:197], v[110:113]
	v_mfma_f32_16x16x32_bf16 v[106:109], v[148:151], v[194:197], v[106:109]
	v_mfma_f32_16x16x32_bf16 v[94:97], v[140:143], v[202:205], v[94:97]
	v_mfma_f32_16x16x32_bf16 v[90:93], v[148:151], v[202:205], v[90:93]
	v_mfma_f32_16x16x32_bf16 v[78:81], v[140:143], v[228:231], v[78:81]
	v_mfma_f32_16x16x32_bf16 v[74:77], v[148:151], v[228:231], v[74:77]
	v_mfma_f32_16x16x32_bf16 v[126:129], v[144:147], v[190:193], v[126:129]
	v_mfma_f32_16x16x32_bf16 v[122:125], v[152:155], v[190:193], v[122:125]
	v_mfma_f32_16x16x32_bf16 v[110:113], v[144:147], v[198:201], v[110:113]
	v_mfma_f32_16x16x32_bf16 v[106:109], v[152:155], v[198:201], v[106:109]
	v_mfma_f32_16x16x32_bf16 v[94:97], v[144:147], v[224:227], v[94:97]
	v_mfma_f32_16x16x32_bf16 v[90:93], v[152:155], v[224:227], v[90:93]
	v_mfma_f32_16x16x32_bf16 v[78:81], v[144:147], v[232:235], v[78:81]
	v_mfma_f32_16x16x32_bf16 v[74:77], v[152:155], v[232:235], v[74:77]
	s_setprio 0
	s_setprio 1
	v_mfma_f32_16x16x32_bf16 v[118:121], v[156:159], v[186:189], v[118:121]
	v_mfma_f32_16x16x32_bf16 v[114:117], v[178:181], v[186:189], v[114:117]
	v_mfma_f32_16x16x32_bf16 v[102:105], v[156:159], v[194:197], v[102:105]
	v_mfma_f32_16x16x32_bf16 v[98:101], v[178:181], v[194:197], v[98:101]
	v_mfma_f32_16x16x32_bf16 v[86:89], v[156:159], v[202:205], v[86:89]
	v_mfma_f32_16x16x32_bf16 v[82:85], v[178:181], v[202:205], v[82:85]
	v_mfma_f32_16x16x32_bf16 v[70:73], v[156:159], v[228:231], v[70:73]
	v_mfma_f32_16x16x32_bf16 v[66:69], v[178:181], v[228:231], v[66:69]
	v_mfma_f32_16x16x32_bf16 v[118:121], v[170:173], v[190:193], v[118:121]
	v_mfma_f32_16x16x32_bf16 v[114:117], v[182:185], v[190:193], v[114:117]
	v_mfma_f32_16x16x32_bf16 v[102:105], v[170:173], v[198:201], v[102:105]
	v_mfma_f32_16x16x32_bf16 v[98:101], v[182:185], v[198:201], v[98:101]
	v_mfma_f32_16x16x32_bf16 v[86:89], v[170:173], v[224:227], v[86:89]
	v_mfma_f32_16x16x32_bf16 v[82:85], v[182:185], v[224:227], v[82:85]
	v_mfma_f32_16x16x32_bf16 v[70:73], v[170:173], v[232:235], v[70:73]
	v_mfma_f32_16x16x32_bf16 v[66:69], v[182:185], v[232:235], v[66:69]
	s_setprio 0
	s_barrier
	s_add_i32 s6, s43, s10
	v_lshl_add_u64 v[206:207], v[206:207], 0, s[60:61]
	s_mov_b32 m0, s6
	ds_read_b128 v[186:189], v177 offset:49152
	ds_read_b128 v[190:193], v177 offset:50176
	ds_read_b128 v[194:197], v177 offset:51200
	ds_read_b128 v[198:201], v177 offset:52224
	ds_read_b128 v[202:205], v177 offset:53248
	ds_read_b128 v[224:227], v177 offset:54272
	ds_read_b128 v[228:231], v177 offset:55296
	ds_read_b128 v[232:235], v177 offset:56320
	global_load_lds_dwordx4 v[206:207], off
	s_add_i32 m0, s6, 0x2000
	s_add_u32 s0, s0, 0x40080
	v_lshl_add_u64 v[206:207], v[236:237], 0, s[60:61]
	s_addc_u32 s1, s1, 0
	s_add_i32 s6, s45, s10
	global_load_lds_dwordx4 v[206:207], off
	v_lshl_add_u64 v[206:207], s[0:1], 0, v[0:1]
	s_mov_b32 m0, s6
	s_nop 0
	global_load_lds_dwordx4 v[206:207], off
	v_lshl_add_u64 v[206:207], s[0:1], 0, v[134:135]
	s_add_i32 m0, s6, 0x2000
	s_nop 0
	global_load_lds_dwordx4 v[206:207], off
	v_lshl_add_u64 v[206:207], v[238:239], 0, s[60:61]
	s_mov_b32 m0, s19
	s_nop 0
	global_load_lds_dwordx4 v[206:207], off
	v_lshl_add_u64 v[206:207], v[240:241], 0, s[60:61]
	s_mov_b32 m0, s20
	s_nop 0
	global_load_lds_dwordx4 v[206:207], off
	s_waitcnt vmcnt(8)
	s_waitcnt lgkmcnt(0)
	s_barrier
	s_setprio 1
	s_waitcnt lgkmcnt(0)
	v_mfma_f32_16x16x32_bf16 v[62:65], v[140:143], v[186:189], v[62:65]
	v_mfma_f32_16x16x32_bf16 v[58:61], v[148:151], v[186:189], v[58:61]
	v_mfma_f32_16x16x32_bf16 v[46:49], v[140:143], v[194:197], v[46:49]
	v_mfma_f32_16x16x32_bf16 v[42:45], v[148:151], v[194:197], v[42:45]
	v_mfma_f32_16x16x32_bf16 v[30:33], v[140:143], v[202:205], v[30:33]
	v_mfma_f32_16x16x32_bf16 v[26:29], v[148:151], v[202:205], v[26:29]
	v_mfma_f32_16x16x32_bf16 v[14:17], v[140:143], v[228:231], v[14:17]
	v_mfma_f32_16x16x32_bf16 v[10:13], v[148:151], v[228:231], v[10:13]
	v_mfma_f32_16x16x32_bf16 v[62:65], v[144:147], v[190:193], v[62:65]
	v_mfma_f32_16x16x32_bf16 v[58:61], v[152:155], v[190:193], v[58:61]
	v_mfma_f32_16x16x32_bf16 v[46:49], v[144:147], v[198:201], v[46:49]
	v_mfma_f32_16x16x32_bf16 v[42:45], v[152:155], v[198:201], v[42:45]
	v_mfma_f32_16x16x32_bf16 v[30:33], v[144:147], v[224:227], v[30:33]
	v_mfma_f32_16x16x32_bf16 v[26:29], v[152:155], v[224:227], v[26:29]
	v_mfma_f32_16x16x32_bf16 v[14:17], v[144:147], v[232:235], v[14:17]
	v_mfma_f32_16x16x32_bf16 v[10:13], v[152:155], v[232:235], v[10:13]
	s_setprio 0
	s_setprio 1
	v_mfma_f32_16x16x32_bf16 v[54:57], v[156:159], v[186:189], v[54:57]
	v_mfma_f32_16x16x32_bf16 v[50:53], v[178:181], v[186:189], v[50:53]
	v_mfma_f32_16x16x32_bf16 v[38:41], v[156:159], v[194:197], v[38:41]
	v_mfma_f32_16x16x32_bf16 v[34:37], v[178:181], v[194:197], v[34:37]
	v_mfma_f32_16x16x32_bf16 v[22:25], v[156:159], v[202:205], v[22:25]
	v_mfma_f32_16x16x32_bf16 v[18:21], v[178:181], v[202:205], v[18:21]
	v_mfma_f32_16x16x32_bf16 v[6:9], v[156:159], v[228:231], v[6:9]
	v_mfma_f32_16x16x32_bf16 v[2:5], v[178:181], v[228:231], v[2:5]
	v_mfma_f32_16x16x32_bf16 v[54:57], v[170:173], v[190:193], v[54:57]
	v_mfma_f32_16x16x32_bf16 v[50:53], v[182:185], v[190:193], v[50:53]
	v_mfma_f32_16x16x32_bf16 v[38:41], v[170:173], v[198:201], v[38:41]
	v_mfma_f32_16x16x32_bf16 v[34:37], v[182:185], v[198:201], v[34:37]
	v_mfma_f32_16x16x32_bf16 v[22:25], v[170:173], v[224:227], v[22:25]
	v_mfma_f32_16x16x32_bf16 v[18:21], v[182:185], v[224:227], v[18:21]
	v_mfma_f32_16x16x32_bf16 v[6:9], v[170:173], v[232:235], v[6:9]
	v_mfma_f32_16x16x32_bf16 v[2:5], v[182:185], v[232:235], v[2:5]
	s_setprio 0
	s_barrier
	s_add_i32 s39, s39, 2
	s_add_u32 s56, s56, 0x100
	s_addc_u32 s57, s57, 0
	s_add_u32 s34, s34, 0x100
	s_addc_u32 s35, s35, 0
	s_cmp_gt_u32 s39, 13
